# lever2: the attention item loop's sink value (loop-invariant per wave when the grid is a multiple of 4) loaded once before the loop; the per-item global load and its vmcnt(0) drain are gone (guarded r
# speedup vs baseline: 1.0010x; 1.0010x over previous
.LBB0_41:
	v_readlane_b32 s26, v252, 30
	v_readlane_b32 s27, v252, 31
	s_lshl_b32 s26, s26, 4
	s_ashr_i32 s27, s26, 31
	s_waitcnt lgkmcnt(0)
	s_add_u32 s20, s20, 0x1b300000
	s_addc_u32 s21, s21, 0
	s_lshl_b64 s[26:27], s[26:27], 2
	v_and_b32_e32 v189, 31, v181
	v_bfe_u32 v190, v181, 5, 1
	s_add_u32 s33, s8, s26
	v_lshlrev_b32_e32 v98, 2, v190
	v_lshrrev_b32_e32 v1, 2, v181
	v_and_b32_e32 v2, 16, v181
	v_lshlrev_b32_e32 v3, 3, v189
	s_addc_u32 s35, s9, s27
	s_bfe_u32 s30, s28, 0x10006
	s_ashr_i32 s36, s28, 7
	s_andn2_b64 vcc, exec, s[6:7]
	v_mul_u32_u24_e32 v99, 0x90, v189
	v_lshlrev_b32_e32 v180, 3, v190
	v_lshlrev_b32_e32 v191, 1, v2
	v_and_b32_e32 v192, 24, v3
	v_and_or_b32 v193, v1, 3, v98
	s_cbranch_vccnz .LBB0_91
	v_and_b32_e32 v1, 0xf8, v188
	s_and_b32 s6, s28, 0xffffff80
	v_lshlrev_b32_e32 v96, 1, v1
	v_mov_b32_e32 v1, v97
	v_add_u32_e32 v196, 0x200, v181
	s_add_i32 s7, s6, 0
	v_lshl_add_u64 v[182:183], s[4:5], 0, v[0:1]
	v_lshl_add_u64 v[184:185], s[16:17], 0, v[0:1]
	v_add_u32_e32 v198, 0x400, v181
	v_ashrrev_i32_e32 v201, 5, v196
	v_mov_b32_e32 v1, s7
	s_movk_i32 s7, 0x210
	v_lshl_or_b32 v2, s30, 5, v189
	v_add_u32_e32 v3, 0, v0
	v_add_u32_e32 v4, 0, v96
	v_add_u32_e32 v194, s67, v96
	v_ashrrev_i32_e32 v202, 5, v198
	v_add_u32_e32 v0, 0x600, v181
	v_mul_lo_u32 v13, v201, s7
	v_ashrrev_i32_e32 v195, 3, v181
	v_ashrrev_i32_e32 v197, 3, v196
	v_ashrrev_i32_e32 v199, 3, v198
	v_ashrrev_i32_e32 v200, 5, v181
	v_ashrrev_i32_e32 v203, 5, v0
	v_mul_u32_u24_e32 v0, 0x210, v2
	v_lshlrev_b32_e32 v5, 4, v190
	s_add_i32 s6, s6, s67
	v_add_u32_e32 v208, v4, v13
	v_add_u32_e32 v209, v194, v13
	v_mul_lo_u32 v13, v202, s7
	v_mad_u32_u24 v1, v2, s7, v1
	v_add_u32_e32 v6, 0, v5
	v_sub_u32_e32 v204, v2, v98
	v_add3_u32 v2, 0, v191, v192
	v_mul_u32_u24_e32 v7, 0xc0, v193
	v_add3_u32 v205, s6, v0, v180
	v_mul_lo_u32 v206, v200, s7
	v_mul_lo_u32 v0, v195, s55
	v_mul_lo_u32 v8, v195, s56
	v_mul_lo_u32 v9, v197, s55
	v_mul_lo_u32 v10, v197, s56
	v_mul_lo_u32 v11, v199, s55
	v_mul_lo_u32 v12, v199, s56
	v_add_u32_e32 v221, v4, v13
	v_add_u32_e32 v222, v194, v13
	v_mul_lo_u32 v13, v203, s7
	v_lshl_add_u64 v[186:187], s[20:21], 0, v[96:97]
	v_add_u32_e32 v207, v4, v206
	v_add_u32_e32 v223, v4, v13
	v_add_u32_e32 v224, v194, v13
	s_sub_i32 s31, 0, s25
	s_sub_i32 s37, 0xfff, s80
	v_add_u32_e32 v225, v3, v0
	v_add_u32_e32 v226, v3, v8
	v_add_u32_e32 v227, v3, v9
	v_add_u32_e32 v228, v3, v10
	v_add_u32_e32 v229, v3, v11
	v_add_u32_e32 v230, v3, v12
	v_add_u32_e32 v231, v1, v5
	v_add_u32_e32 v232, v6, v99
	v_add_u32_e32 v233, v2, v7
	s_mov_b32 s38, s80
	s_and_b64 s[6:7], s[82:83], exec
	s_cselect_b32 s6, s37, s80
	s_and_b32 s6, s6, 3
	s_lshl_b32 s6, s6, 2
	s_add_i32 s6, s6, s36
	s_ashr_i32 s7, s6, 31
	s_lshl_b64 s[6:7], s[6:7], 2
	s_add_u32 s6, s33, s6
	s_addc_u32 s7, s35, s7
	global_load_dword v248, v97, s[6:7]
	s_branch .LBB0_44

.LBB0_67:
	s_and_b32 s28, s40, 3
	s_lshl_b32 s29, s28, 2
	s_add_i32 s42, s29, s36
	s_add_i32 s29, s42, 1
	v_cvt_f32_i32_e32 v156, s29
	v_lshl_add_u32 v158, s41, 6, v204
	v_cvt_f32_i32_e32 v158, v158
	v_mul_f32_e32 v157, -0.5, v156
	v_cmp_gt_f32_e32 vcc, s57, v157
	s_and_b64 s[44:45], vcc, exec
	s_cselect_b32 s29, 0xffffffc0, 0
	s_ashr_i32 s43, s42, 31
	s_lshl_b64 s[42:43], s[42:43], 2
	v_cndmask_b32_e32 v157, 0, v215, vcc
	s_add_u32 s42, s33, s42
	v_fmac_f32_e32 v157, -0.5, v156
	s_addc_u32 s43, s35, s43
	v_exp_f32_e32 v156, v157
	s_and_b32 s44, s25, 3
	s_cmp_eq_u32 s44, 0
	s_cbranch_scc1 .Lsink_ok
	global_load_dword v248, v97, s[42:43]
	s_waitcnt vmcnt(0)
.Lsink_ok:
	s_and_b64 vcc, exec, s[8:9]
	v_ldexp_f32 v156, v156, s29
	v_mul_f32_e32 v156, 0x3fb8aa3b, v156
	v_add_f32_e32 v159, -1.0, v158
	v_fma_f32 v81, -v156, |v159|, v81
	v_add_f32_e32 v159, -2.0, v158
	v_fma_f32 v82, -v156, |v159|, v82
	v_add_f32_e32 v159, 0xc0400000, v158
	v_fma_f32 v83, -v156, |v159|, v83
	v_add_f32_e32 v159, 0xc1000000, v158
	v_fma_f32 v84, -v156, |v159|, v84
	v_add_f32_e32 v159, 0xc1100000, v158
	v_fma_f32 v85, -v156, |v159|, v85
	v_add_f32_e32 v159, 0xc1200000, v158
	v_fma_f32 v86, -v156, |v159|, v86
	v_add_f32_e32 v159, 0xc1300000, v158
	v_fma_f32 v87, -v156, |v159|, v87
	v_add_f32_e32 v159, 0xc1800000, v158
	v_fma_f32 v88, -v156, |v159|, v88
	v_add_f32_e32 v159, 0xc1880000, v158
	v_fma_f32 v89, -v156, |v159|, v89
	v_add_f32_e32 v159, 0xc1900000, v158
	v_fma_f32 v90, -v156, |v159|, v90
	v_add_f32_e32 v159, 0xc1980000, v158
	v_fma_f32 v91, -v156, |v159|, v91
	v_add_f32_e32 v159, 0xc1c00000, v158
	v_fma_f32 v92, -v156, |v159|, v92
	v_add_f32_e32 v159, 0xc1c80000, v158
	v_fma_f32 v93, -v156, |v159|, v93
	v_add_f32_e32 v159, 0xc1d00000, v158
	v_add_f32_e32 v160, 0xc2000000, v158
	v_fma_f32 v80, -v156, |v158|, v80
	v_fma_f32 v94, -v156, |v159|, v94
	v_add_f32_e32 v159, 0xc1d80000, v158
	v_fma_f32 v64, -v156, |v160|, v64
	v_add_f32_e32 v160, 0xc2040000, v158
	v_fma_f32 v95, -v156, |v159|, v95
	v_fma_f32 v65, -v156, |v160|, v65
	v_add_f32_e32 v160, 0xc2080000, v158
	v_fma_f32 v66, -v156, |v160|, v66
	v_add_f32_e32 v160, 0xc20c0000, v158
	v_fma_f32 v67, -v156, |v160|, v67
	v_add_f32_e32 v160, 0xc2200000, v158
	v_fma_f32 v68, -v156, |v160|, v68
	v_add_f32_e32 v160, 0xc2240000, v158
	v_fma_f32 v69, -v156, |v160|, v69
	v_add_f32_e32 v160, 0xc2280000, v158
	v_fma_f32 v70, -v156, |v160|, v70
	v_add_f32_e32 v160, 0xc22c0000, v158
	v_fma_f32 v71, -v156, |v160|, v71
	v_add_f32_e32 v160, 0xc2400000, v158
	v_fma_f32 v72, -v156, |v160|, v72
	v_add_f32_e32 v160, 0xc2440000, v158
	v_fma_f32 v73, -v156, |v160|, v73
	v_add_f32_e32 v160, 0xc2480000, v158
	v_fma_f32 v74, -v156, |v160|, v74
	v_add_f32_e32 v160, 0xc24c0000, v158
	v_fma_f32 v75, -v156, |v160|, v75
	v_add_f32_e32 v160, 0xc2600000, v158
	v_fma_f32 v76, -v156, |v160|, v76
	v_add_f32_e32 v160, 0xc2640000, v158
	v_fma_f32 v77, -v156, |v160|, v77
	v_add_f32_e32 v160, 0xc2680000, v158
	v_fma_f32 v78, -v156, |v160|, v78
	v_add_f32_e32 v160, 0xc26c0000, v158
	v_fma_f32 v79, -v156, |v160|, v79
	v_mul_f32_e32 v157, 0x3fb8aa3b, v248
	v_max3_f32 v159, v157, v80, v81
	v_max3_f32 v159, v159, v82, v83
	v_max3_f32 v159, v159, v84, v85
	v_max3_f32 v159, v159, v86, v87
	v_max3_f32 v159, v159, v88, v89
	v_max3_f32 v159, v159, v90, v91
	v_max3_f32 v159, v159, v92, v93
	v_max3_f32 v159, v159, v94, v95
	v_max3_f32 v159, v159, v64, v65
	v_max3_f32 v159, v159, v66, v67
	v_max3_f32 v159, v159, v68, v69
	v_max3_f32 v159, v159, v70, v71
	v_max3_f32 v159, v159, v72, v73
	v_max3_f32 v159, v159, v74, v75
	v_max3_f32 v159, v159, v76, v77
	v_max3_f32 v160, v159, v78, v79
	s_cbranch_vccnz .LBB0_69
	v_pk_add_f32 v[162:163], v[158:159], s[68:69] op_sel_hi:[0,1]
	v_and_b32_e32 v163, 0x7fffffff, v163
	v_and_b32_e32 v162, 0x7fffffff, v162
	v_pk_fma_f32 v[48:49], v[156:157], v[162:163], v[48:49] op_sel_hi:[0,1,1] neg_lo:[1,0,0] neg_hi:[1,0,0]
	v_max3_f32 v159, v160, v48, v49
	v_pk_add_f32 v[160:161], v[158:159], s[70:71] op_sel_hi:[0,1]
	v_and_b32_e32 v161, 0x7fffffff, v161
	v_and_b32_e32 v160, 0x7fffffff, v160
	v_pk_fma_f32 v[50:51], v[156:157], v[160:161], v[50:51] op_sel_hi:[0,1,1] neg_lo:[1,0,0] neg_hi:[1,0,0]
	s_mov_b32 s42, 0xc2900000
	v_max3_f32 v159, v159, v50, v51
	s_mov_b32 s43, 0xc2920000
	v_pk_add_f32 v[160:161], v[158:159], s[42:43] op_sel_hi:[0,1]
	v_and_b32_e32 v161, 0x7fffffff, v161
	v_and_b32_e32 v160, 0x7fffffff, v160
	v_pk_fma_f32 v[52:53], v[156:157], v[160:161], v[52:53] op_sel_hi:[0,1,1] neg_lo:[1,0,0] neg_hi:[1,0,0]
	s_mov_b32 s42, 0xc2940000
	v_max3_f32 v159, v159, v52, v53
	s_mov_b32 s43, 0xc2960000
	v_pk_add_f32 v[160:161], v[158:159], s[42:43] op_sel_hi:[0,1]
	v_and_b32_e32 v161, 0x7fffffff, v161
	v_and_b32_e32 v160, 0x7fffffff, v160
	v_pk_fma_f32 v[54:55], v[156:157], v[160:161], v[54:55] op_sel_hi:[0,1,1] neg_lo:[1,0,0] neg_hi:[1,0,0]
	s_mov_b32 s42, 0xc2a00000
	v_max3_f32 v159, v159, v54, v55
	s_mov_b32 s43, 0xc2a20000
	v_pk_add_f32 v[160:161], v[158:159], s[42:43] op_sel_hi:[0,1]
	v_and_b32_e32 v161, 0x7fffffff, v161
	v_and_b32_e32 v160, 0x7fffffff, v160
	v_pk_fma_f32 v[56:57], v[156:157], v[160:161], v[56:57] op_sel_hi:[0,1,1] neg_lo:[1,0,0] neg_hi:[1,0,0]
	s_mov_b32 s42, 0xc2a40000
	v_max3_f32 v159, v159, v56, v57
	s_mov_b32 s43, 0xc2a60000
	v_pk_add_f32 v[160:161], v[158:159], s[42:43] op_sel_hi:[0,1]
	v_and_b32_e32 v161, 0x7fffffff, v161
	v_and_b32_e32 v160, 0x7fffffff, v160
	v_pk_fma_f32 v[58:59], v[156:157], v[160:161], v[58:59] op_sel_hi:[0,1,1] neg_lo:[1,0,0] neg_hi:[1,0,0]
	s_mov_b32 s42, 0xc2b00000
	v_max3_f32 v159, v159, v58, v59
	s_mov_b32 s43, 0xc2b20000
	v_pk_add_f32 v[160:161], v[158:159], s[42:43] op_sel_hi:[0,1]
	v_and_b32_e32 v161, 0x7fffffff, v161
	v_and_b32_e32 v160, 0x7fffffff, v160
	v_pk_fma_f32 v[60:61], v[156:157], v[160:161], v[60:61] op_sel_hi:[0,1,1] neg_lo:[1,0,0] neg_hi:[1,0,0]
	s_mov_b32 s42, 0xc2b40000
	v_max3_f32 v159, v159, v60, v61
	s_mov_b32 s43, 0xc2b60000
	v_pk_add_f32 v[160:161], v[158:159], s[42:43] op_sel_hi:[0,1]
	v_and_b32_e32 v161, 0x7fffffff, v161
	v_and_b32_e32 v160, 0x7fffffff, v160
	v_pk_fma_f32 v[62:63], v[156:157], v[160:161], v[62:63] op_sel_hi:[0,1,1] neg_lo:[1,0,0] neg_hi:[1,0,0]
	v_max3_f32 v160, v159, v62, v63
